# v10 + P8->P9 seam: grid barrier replaced by a 32-workgroup row-group barrier (H rows produced and consumed by the same XCD group); other grids keep the grid barrier
# speedup vs baseline: 1.0047x; 1.0020x over previous
.LBB0_879:
	s_waitcnt vmcnt(0)
	s_cmp_gt_i32 s73, 9
	s_cselect_b64 s[6:7], -1, 0
	s_and_b64 s[2:3], s[4:5], s[6:7]
	s_andn2_b64 vcc, exec, s[2:3]
	s_cbranch_vccnz .LBB0_933
	s_cmpk_lg_i32 s80, 0x100
	s_cbranch_scc1 .Lgb_orig_0
	s_waitcnt vmcnt(0)
	s_barrier
	s_and_saveexec_b64 s[4:5], s[86:87]
	s_cbranch_execz .Lgb_done_0
	buffer_wbl2 sc1
	s_waitcnt vmcnt(0)
	s_and_b32 s2, s76, 7
	s_lshl_b32 s2, s2, 8
	s_add_u32 s8, s74, s2
	s_addc_u32 s9, s75, 0
	v_mov_b32_e32 v2, 0x5000
	v_mov_b32_e32 v3, 1
	global_atomic_add v2, v3, s[8:9]
	s_mov_b32 s3, 0
.Lgb_spin_0:
	global_load_dword v4, v2, s[8:9] sc1
	s_add_i32 s3, s3, 1
	s_waitcnt vmcnt(0)
	v_cmp_gt_u32_e32 vcc, 32, v4
	s_cbranch_vccz .Lgb_out_0
	s_sleep 1
	s_cmp_lt_u32 s3, 0x20000
	s_cbranch_scc1 .Lgb_spin_0
.Lgb_out_0:
	buffer_inv sc1
	s_waitcnt vmcnt(0)
.Lgb_done_0:
	s_or_b64 exec, exec, s[4:5]
	s_barrier
	s_branch .LBB0_933
.Lgb_orig_0:
	s_waitcnt vmcnt(0)
	s_waitcnt vmcnt(0)
	s_barrier
	s_and_saveexec_b64 s[4:5], s[86:87]
	s_cbranch_execz .LBB0_932
	s_add_i32 s2, 0, 0x25f00
	v_mov_b32_e32 v2, s2
	s_waitcnt vmcnt(0) expcnt(0) lgkmcnt(0)
	ds_read_b32 v4, v2
	s_add_i32 s2, 0, 0x25f04
	v_mov_b32_e32 v2, s2
	ds_read_b32 v2, v2
	s_waitcnt lgkmcnt(1)
	v_cmp_ne_u32_e32 vcc, 0, v4
	s_cbranch_vccnz .LBB0_896
	v_readlane_b32 s8, v250, 0
	v_readlane_b32 s9, v250, 1
	s_load_dwordx2 s[2:3], s[8:9], 0x4
	s_add_u32 s8, s74, 0x1000
	s_addc_u32 s9, s75, 0
	s_add_u32 s10, s74, 0x1100
	s_addc_u32 s11, s75, 0
	s_add_u32 s12, s74, 0x1200
	s_addc_u32 s13, s75, 0
	s_waitcnt lgkmcnt(0)
	s_mul_i32 s2, s2, s80
	s_add_u32 s14, s74, 0x1300
	s_mul_i32 s2, s2, s3
	s_addc_u32 s15, s75, 0
	s_mov_b32 s3, 1
	v_mov_b32_e32 v18, 0
	s_branch .LBB0_884
